# token-major in-proj: column-tile positions 2 and 7 swapped so the two rotary tiles go to workgroups with one unit of slack
# speedup vs baseline: 1.0269x; 1.0026x over previous
;     __host__ __device__ bool next(int i, Unit& u) const {
;         const long L = (long)i * G + c; if (L >= nwg) return false;
;         int wgid = (int)L; { const int q = nwg / NXCD, r = nwg % NXCD, xcd = wgid % NXCD, off = wgid / NXCD; wgid = (xcd < r ? xcd * (q + 1) : r * (q + 1) + (xcd - r) * q) + off; }
;         const int nig = WGM * nN, gid = wgid / nig, fm = gid * WGM, gsz = (nM - fm) < WGM ? (nM - fm) : WGM;
;         u.pm = fm + ((wgid % nig) % gsz); u.pn = (wgid % nig) / gsz; return true;
.LBB0_498:
	s_cmpk_lt_i32 s2, 0x480
	s_cselect_b64 s[4:5], -1, 0
	s_cmpk_gt_i32 s2, 0x47f
	v_readfirstlane_b32 s14, v254
	s_waitcnt lgkmcnt(0)
	s_barrier
	s_cbranch_scc1 .LBB0_500
	s_lshr_b32 s6, s3, 29
	s_add_i32 s6, s2, s6
	s_ashr_i32 s7, s6, 3
	s_and_b32 s6, s6, -8
	s_sub_i32 s6, s2, s6
	s_cmp_lt_i32 s6, 0
	s_movk_i32 s8, 0x91
	s_cselect_b32 s8, s8, 0x90
	s_mul_i32 s6, s8, s6
	s_add_i32 s6, s6, s7
	s_mul_hi_i32 s7, s6, 0x38e38e39
	s_lshr_b32 s8, s7, 31
	s_ashr_i32 s7, s7, 4
	s_add_i32 s7, s7, s8
	s_lshl_b32 s8, s7, 3
	s_mulk_i32 s7, 0x48
	s_sub_i32 s6, s6, s7
	s_bfe_i32 s7, s6, 0x80000
	s_bfe_u32 s7, s7, 0x3000c
	s_add_i32 s7, s6, s7
	s_bfe_i32 s9, s7, 0x80000
	s_and_b32 s7, s7, 0xf8
	s_sub_i32 s6, s6, s7
	s_sext_i32_i16 s9, s9
	s_sext_i32_i8 s6, s6
	s_add_i32 s8, s8, s6
	s_ashr_i32 s6, s9, 3
	s_cmp_eq_u32 s6, 2
	s_cselect_b32 s7, 7, s6
	s_cmp_eq_u32 s6, 7
	s_cselect_b32 s6, 2, s7

; #define PG8_STAGE(bufoff, gbase, voff) do { _Pragma("unroll") for (int _i = 0; _i < 2; ++_i) \
;         __builtin_amdgcn_global_load_lds((const unsigned*)((const char*)(gbase) + (voff)[_i]), (PG8_LAS unsigned*)(lds + (bufoff) + ldsw + _i * 8192), 16, 0, 0); } while (0)
; #define PG8_LDA(dst, b, h) do { _Pragma("unroll") for (int m = 0; m < 4; ++m) _Pragma("unroll") for (int k = 0; k < 2; ++k) dst[m][k] = *(const PG8_LAS bf16x8*)(lds + PG8_SA(b, h) + aoff + m * 2048 + k * 1024); } while (0)
; #define PG8_LDB(dst, b, h) do { _Pragma("unroll") for (int n = 0; n < 2; ++n) _Pragma("unroll") for (int k = 0; k < 2; ++k) dst[n][k] = *(const PG8_LAS bf16x8*)(lds + PG8_SB(b, h) + boff + n * 2048 + k * 1024); } while (0)
; #define PG8_SCHED __builtin_amdgcn_sched_barrier(0)
;     __host__ __device__ bool next(int i, Unit& u) const {
;         const long L = (long)i * G + c; if (L >= nwg) return false;
;         int wgid = (int)L; { const int q = nwg / NXCD, r = nwg % NXCD, xcd = wgid % NXCD, off = wgid / NXCD; wgid = (xcd < r ? xcd * (q + 1) : r * (q + 1) + (xcd - r) * q) + off; }
;         const int nig = WGM * nN, gid = wgid / nig, fm = gid * WGM, gsz = (nM - fm) < WGM ? (nM - fm) : WGM;
;         u.pm = fm + ((wgid % nig) % gsz); u.pn = (wgid % nig) / gsz; return true;
; template <class Epi, class Sched, bool ALIGN_EPI = false, bool SP2 = false>
; __device__ __forceinline__ void gemm_phase(PG8_LAS unsigned char* lds, const Gemm g, const Sched& S, const Epi& E) {
;     ...
;         const bool has_next = S.next(ui + 1, nxt);
;         const char* nA = has_next ? (const char*)g.A + (size_t)nxt.pm * tstep : cA; const char* nB = has_next ? (const char*)g.Bt + (size_t)nxt.pn * tstep : cB;
;         for (int t = 0; t < nt; t += 2) {
;             const bool last = (t == nt - 2);
;             const char* a1 = cA + (size_t)(t + 1) * kstep;
;             const char* a2 = last ? nA : cA + (size_t)(t + 2) * kstep; const char* b2 = last ? nB : cB + (size_t)(t + 2) * kstep;
;             const char* a3 = a2 + kstep; const char* b3 = b2 + kstep;
;             if (last && has_next) S.a_ready(nxt, ui + 1);
;             if constexpr (SP2) {
;             PG8_LDB(B0, 0, 0); PG8_LDB(B1, 0, 1); PG8_SCHED; PG8_LDA(At, 0, 0); PG8_STAGE(PG8_SA(1, 1), a1 + hstep, voffA);
.LBB0_506:
	ds_read_b128 v[148:151], v162
	ds_read_b128 v[166:169], v162 offset:1024
	ds_read_b128 v[170:173], v162 offset:2048
	ds_read_b128 v[174:177], v162 offset:3072
	ds_read_b128 v[178:181], v163
	ds_read_b128 v[182:185], v163 offset:1024
	ds_read_b128 v[186:189], v163 offset:2048
	ds_read_b128 v[190:193], v163 offset:3072
	ds_read_b128 v[194:197], v164
	ds_read_b128 v[198:201], v164 offset:1024
	ds_read_b128 v[202:205], v164 offset:2048
	ds_read_b128 v[206:209], v164 offset:3072
	ds_read_b128 v[210:213], v164 offset:4096
	ds_read_b128 v[214:217], v164 offset:5120
	ds_read_b128 v[218:221], v164 offset:6144
	ds_read_b128 v[222:225], v164 offset:7168
	s_add_i32 s69, s7, 1
	s_mul_i32 s4, s69, s46
	s_mul_hi_u32 s5, s69, s47
	s_add_i32 s5, s5, s4
	s_mul_i32 s4, s69, s47
	s_add_u32 s34, s4, s2
	s_addc_u32 s35, s5, s3
	v_cmp_gt_i64_e32 vcc, s[34:35], v[146:147]
	v_cmp_lt_i64_e64 s[4:5], s[34:35], v[144:145]
	s_cbranch_vccnz .LBB0_508
	s_ashr_i32 s9, s34, 31
	s_lshr_b32 s9, s9, 29
	s_add_i32 s9, s34, s9
	s_ashr_i32 s14, s9, 3
	s_and_b32 s9, s9, -8
	s_sub_i32 s9, s34, s9
	s_cmp_lt_i32 s9, 0
	s_cselect_b32 s28, s60, 0x90
	s_mul_i32 s9, s28, s9
	s_add_i32 s9, s9, s14
	s_mul_hi_i32 s14, s9, 0x38e38e39
	s_lshr_b32 s28, s14, 31
	s_ashr_i32 s14, s14, 4
	s_add_i32 s14, s14, s28
	s_lshl_b32 s29, s14, 3
	s_sub_i32 s28, 0x80, s29
	s_min_i32 s30, s28, 8
	s_abs_i32 s28, s30
	v_cvt_f32_u32_e32 v0, s28
	s_sub_i32 s34, 0, s28
	s_mulk_i32 s14, 0x48
	s_sub_i32 s9, s9, s14
	v_rcp_iflag_f32_e32 v0, v0
	s_abs_i32 s14, s9
	s_xor_b32 s31, s9, s30
	s_ashr_i32 s31, s31, 31
	v_mul_f32_e32 v0, 0x4f7ffffe, v0
	v_cvt_u32_f32_e32 v0, v0
	s_nop 0
	v_readfirstlane_b32 s35, v0
	s_mul_i32 s34, s34, s35
	s_mul_hi_u32 s34, s35, s34
	s_add_i32 s35, s35, s34
	s_mul_hi_u32 s34, s14, s35
	s_mul_i32 s35, s34, s28
	s_sub_i32 s14, s14, s35
	s_add_i32 s36, s34, 1
	s_sub_i32 s35, s14, s28
	s_cmp_ge_u32 s14, s28
	s_cselect_b32 s34, s36, s34
	s_cselect_b32 s14, s35, s14
	s_add_i32 s35, s34, 1
	s_cmp_ge_u32 s14, s28
	s_cselect_b32 s14, s35, s34
	s_xor_b32 s14, s14, s31
	s_sub_i32 s28, s14, s31
	s_mul_i32 s14, s28, s30
	s_sub_i32 s9, s9, s14
	s_add_i32 s30, s9, s29
	s_cmp_eq_u32 s28, 2
	s_cselect_b32 s9, 7, s28
	s_cmp_eq_u32 s28, 7
	s_cselect_b32 s28, 2, s9
